# tile headers: next unit = same row panel, column tile + 4 when gridDim is 256 (generic unit decode kept for other grids)
# speedup vs baseline: 1.0092x; 1.0025x over previous
.LBB0_285:
	s_add_i32 s54, s9, 1
	s_mul_i32 s6, s54, s52
	s_mul_hi_u32 s7, s54, s98
	s_add_i32 s7, s7, s6
	s_mul_i32 s6, s54, s98
	v_readlane_b32 s22, v254, 47
	v_readlane_b32 s23, v254, 48
	s_add_u32 s22, s6, s22
	s_addc_u32 s23, s7, s53
	v_cmp_gt_i64_e32 vcc, s[22:23], v[212:213]
	v_cmp_lt_i64_e64 s[6:7], s[22:23], v[210:211]
	s_cbranch_vccnz .LBB0_287
	s_cmpk_lg_i32 s98, 0x100
	s_cbranch_scc1 .Lkq_dec_gen
	s_add_i32 s18, s26, 4
	s_mov_b32 s20, s8
	s_branch .LBB0_287
.Lkq_dec_gen:
	s_ashr_i32 s18, s22, 31
	s_lshr_b32 s18, s18, 29
	s_add_i32 s18, s22, s18
	s_ashr_i32 s19, s18, 3
	s_and_b32 s18, s18, -8
	s_sub_i32 s18, s22, s18
	s_cmp_lt_i32 s18, 0
	s_movk_i32 s20, 0x61
	s_cselect_b32 s20, s20, 0x60
	s_mul_i32 s18, s18, s20
	s_add_i32 s18, s18, s19
	s_mul_hi_i32 s19, s18, 0x2aaaaaab
	s_lshr_b32 s20, s19, 31
	s_ashr_i32 s19, s19, 4
	s_add_i32 s19, s19, s20
	s_lshl_b32 s20, s19, 3
	s_sub_i32 s21, 64, s20
	s_min_i32 s21, s21, 8
	s_abs_i32 s22, s21
	v_cvt_f32_u32_e32 v2, s22
	s_sub_i32 s24, 0, s22
	s_mulk_i32 s19, 0x60
	s_sub_i32 s19, s18, s19
	v_rcp_iflag_f32_e32 v2, v2
	s_abs_i32 s18, s19
	s_xor_b32 s23, s19, s21
	s_ashr_i32 s23, s23, 31
	v_mul_f32_e32 v2, 0x4f7ffffe, v2
	v_cvt_u32_f32_e32 v2, v2
	s_nop 0
	v_readfirstlane_b32 s25, v2
	s_mul_i32 s24, s24, s25
	s_mul_hi_u32 s24, s25, s24
	s_add_i32 s25, s25, s24
	s_mul_hi_u32 s24, s18, s25
	s_mul_i32 s25, s24, s22
	s_sub_i32 s18, s18, s25
	s_add_i32 s34, s24, 1
	s_sub_i32 s25, s18, s22
	s_cmp_ge_u32 s18, s22
	s_cselect_b32 s24, s34, s24
	s_cselect_b32 s18, s25, s18
	s_add_i32 s25, s24, 1
	s_cmp_ge_u32 s18, s22
	s_cselect_b32 s18, s25, s24
	s_xor_b32 s18, s18, s23
	s_sub_i32 s18, s18, s23
	s_mul_i32 s21, s18, s21
	s_sub_i32 s19, s19, s21
	s_add_i32 s20, s20, s19
.LBB0_287:
	s_ashr_i32 s21, s20, 31
	s_lshl_b64 s[22:23], s[20:21], 19
	s_add_u32 s22, s80, s22
	s_addc_u32 s23, s81, s23
	s_and_b64 s[24:25], s[6:7], exec
	s_cselect_b32 s21, s23, s29
	s_cselect_b32 s36, s22, s28
	s_ashr_i32 s19, s18, 31
	s_lshl_b64 s[24:25], s[18:19], 19
	s_add_u32 s24, s40, s24
	s_addc_u32 s25, s41, s25
	s_and_b64 s[34:35], s[6:7], exec
	s_cselect_b32 s19, s25, s31
	s_cselect_b32 s37, s24, s30
	s_add_u32 s38, s30, 0x100
	s_addc_u32 s39, s31, 0
	s_add_u32 s28, s28, 0x40080
	s_addc_u32 s29, s29, 0
	s_mov_b32 s55, -2
	s_add_u32 s30, s28, 0xfffc0080
	s_addc_u32 s31, s29, -1
	s_add_i32 s56, 0, 0x10000
	s_cmp_eq_u32 s55, 12
	s_cselect_b32 s35, s21, s31
	s_cselect_b32 s34, s36, s30
	s_cselect_b32 s31, s19, s39
	s_cselect_b32 s30, s37, s38
	s_add_i32 s58, 0, 0x14000
	v_add_u32_e32 v166, s56, v147
	v_add_u32_e32 v182, s58, v147
	ds_read_b128 v[142:145], v166
	ds_read_b128 v[158:161], v166 offset:1024
	ds_read_b128 v[162:165], v166 offset:2048
	ds_read_b128 v[166:169], v166 offset:3072
	ds_read_b128 v[170:173], v182
	ds_read_b128 v[174:177], v182 offset:1024
	ds_read_b128 v[178:181], v182 offset:2048
	ds_read_b128 v[182:185], v182 offset:3072
	v_lshl_add_u64 v[224:225], s[28:29], 0, v[140:141]
	s_add_i32 m0, s44, 0xc000
	ds_read_b128 v[186:189], v157
	ds_read_b128 v[190:193], v157 offset:1024
	ds_read_b128 v[194:197], v157 offset:2048
	ds_read_b128 v[198:201], v157 offset:3072
	ds_read_b128 v[202:205], v157 offset:4096
	ds_read_b128 v[206:209], v157 offset:5120
	ds_read_b128 v[220:223], v157 offset:6144
	ds_read_b128 v[236:239], v157 offset:7168
	global_load_lds_dwordx4 v[224:225], off
	v_lshl_add_u64 v[224:225], s[28:29], 0, v[138:139]
	s_add_i32 m0, s44, 0xe000
	s_nop 0
	global_load_lds_dwordx4 v[224:225], off
	s_nop 0
	s_nop 0
	s_nop 0
	s_nop 0
	s_nop 0
	s_nop 0
	s_nop 0
	s_nop 0
	s_nop 0
	s_nop 0
	s_nop 0
	s_nop 0
	s_nop 0
	s_nop 0
	s_nop 0
	s_nop 0
	s_nop 0
	s_nop 0
	s_nop 0
	s_waitcnt vmcnt(8)
	s_waitcnt lgkmcnt(0)
	s_barrier
	s_waitcnt lgkmcnt(0)
	v_mfma_f32_16x16x32_bf16 v[126:129], v[142:145], v[186:189], 0
	v_mfma_f32_16x16x32_bf16 v[122:125], v[162:165], v[186:189], 0
	v_mfma_f32_16x16x32_bf16 v[110:113], v[142:145], v[194:197], 0
	v_mfma_f32_16x16x32_bf16 v[106:109], v[162:165], v[194:197], 0
	v_mfma_f32_16x16x32_bf16 v[94:97], v[142:145], v[202:205], 0
	v_mfma_f32_16x16x32_bf16 v[90:93], v[162:165], v[202:205], 0
	v_mfma_f32_16x16x32_bf16 v[78:81], v[142:145], v[220:223], 0
	v_mfma_f32_16x16x32_bf16 v[74:77], v[162:165], v[220:223], 0
	v_mfma_f32_16x16x32_bf16 v[126:129], v[158:161], v[190:193], v[126:129]
	v_mfma_f32_16x16x32_bf16 v[122:125], v[166:169], v[190:193], v[122:125]
	v_mfma_f32_16x16x32_bf16 v[110:113], v[158:161], v[198:201], v[110:113]
	v_mfma_f32_16x16x32_bf16 v[106:109], v[166:169], v[198:201], v[106:109]
	v_mfma_f32_16x16x32_bf16 v[94:97], v[158:161], v[206:209], v[94:97]
	v_mfma_f32_16x16x32_bf16 v[90:93], v[166:169], v[206:209], v[90:93]
	v_mfma_f32_16x16x32_bf16 v[78:81], v[158:161], v[236:239], v[78:81]
	v_mfma_f32_16x16x32_bf16 v[74:77], v[166:169], v[236:239], v[74:77]
	v_mfma_f32_16x16x32_bf16 v[118:121], v[170:173], v[186:189], 0
	v_mfma_f32_16x16x32_bf16 v[114:117], v[178:181], v[186:189], 0
	v_mfma_f32_16x16x32_bf16 v[102:105], v[170:173], v[194:197], 0
	v_mfma_f32_16x16x32_bf16 v[98:101], v[178:181], v[194:197], 0
	v_mfma_f32_16x16x32_bf16 v[86:89], v[170:173], v[202:205], 0
	v_mfma_f32_16x16x32_bf16 v[82:85], v[178:181], v[202:205], 0
	v_mfma_f32_16x16x32_bf16 v[70:73], v[170:173], v[220:223], 0
	v_mfma_f32_16x16x32_bf16 v[66:69], v[178:181], v[220:223], 0
	v_mfma_f32_16x16x32_bf16 v[118:121], v[174:177], v[190:193], v[118:121]
	v_mfma_f32_16x16x32_bf16 v[114:117], v[182:185], v[190:193], v[114:117]
	v_mfma_f32_16x16x32_bf16 v[102:105], v[174:177], v[198:201], v[102:105]
	v_mfma_f32_16x16x32_bf16 v[98:101], v[182:185], v[198:201], v[98:101]
	v_mfma_f32_16x16x32_bf16 v[86:89], v[174:177], v[206:209], v[86:89]
	v_mfma_f32_16x16x32_bf16 v[82:85], v[182:185], v[206:209], v[82:85]
	v_mfma_f32_16x16x32_bf16 v[70:73], v[174:177], v[236:239], v[70:73]
	v_mfma_f32_16x16x32_bf16 v[66:69], v[182:185], v[236:239], v[66:69]
	s_barrier
	s_add_i32 s56, s56, s27
	v_lshl_add_u64 v[224:225], s[30:31], 0, v[132:133]
	s_mov_b32 m0, s56
	ds_read_b128 v[186:189], v157 offset:16384
	ds_read_b128 v[190:193], v157 offset:17408
	ds_read_b128 v[194:197], v157 offset:18432
	ds_read_b128 v[198:201], v157 offset:19456
	ds_read_b128 v[202:205], v157 offset:20480
	ds_read_b128 v[206:209], v157 offset:21504
	ds_read_b128 v[220:223], v157 offset:22528
	ds_read_b128 v[236:239], v157 offset:23552
	global_load_lds_dwordx4 v[224:225], off
	s_add_i32 m0, s56, 0x2000
	s_add_u32 s56, s30, 0x40000
	v_lshl_add_u64 v[230:231], s[30:31], 0, v[136:137]
	s_addc_u32 s57, s31, 0
	s_add_i32 s58, s58, s27
	global_load_lds_dwordx4 v[230:231], off
	v_lshl_add_u64 v[240:241], s[56:57], 0, v[132:133]
	s_mov_b32 m0, s58
	v_lshl_add_u64 v[242:243], s[34:35], 0, v[134:135]
	global_load_lds_dwordx4 v[240:241], off
	v_lshl_add_u64 v[240:241], s[56:57], 0, v[136:137]
	s_add_i32 m0, s58, 0x2000
	s_nop 0
	global_load_lds_dwordx4 v[240:241], off
	v_lshl_add_u64 v[240:241], s[34:35], 0, v[130:131]
	s_mov_b32 m0, s44
	s_nop 0
	global_load_lds_dwordx4 v[240:241], off
	s_mov_b32 m0, s45
	s_nop 0
	global_load_lds_dwordx4 v[242:243], off
	s_nop 0
	s_nop 0
	s_nop 0
	s_waitcnt vmcnt(8)
	s_waitcnt lgkmcnt(0)
	s_barrier
	s_waitcnt lgkmcnt(0)
	v_mfma_f32_16x16x32_bf16 v[62:65], v[142:145], v[186:189], 0
	v_mfma_f32_16x16x32_bf16 v[58:61], v[162:165], v[186:189], 0
	v_mfma_f32_16x16x32_bf16 v[46:49], v[142:145], v[194:197], 0
	v_mfma_f32_16x16x32_bf16 v[42:45], v[162:165], v[194:197], 0
	v_mfma_f32_16x16x32_bf16 v[30:33], v[142:145], v[202:205], 0
	v_mfma_f32_16x16x32_bf16 v[26:29], v[162:165], v[202:205], 0
	v_mfma_f32_16x16x32_bf16 v[14:17], v[142:145], v[220:223], 0
	v_mfma_f32_16x16x32_bf16 v[10:13], v[162:165], v[220:223], 0
	v_mfma_f32_16x16x32_bf16 v[62:65], v[158:161], v[190:193], v[62:65]
	v_mfma_f32_16x16x32_bf16 v[58:61], v[166:169], v[190:193], v[58:61]
	v_mfma_f32_16x16x32_bf16 v[46:49], v[158:161], v[198:201], v[46:49]
	v_mfma_f32_16x16x32_bf16 v[42:45], v[166:169], v[198:201], v[42:45]
	v_mfma_f32_16x16x32_bf16 v[30:33], v[158:161], v[206:209], v[30:33]
	v_mfma_f32_16x16x32_bf16 v[26:29], v[166:169], v[206:209], v[26:29]
	v_mfma_f32_16x16x32_bf16 v[14:17], v[158:161], v[236:239], v[14:17]
	v_mfma_f32_16x16x32_bf16 v[10:13], v[166:169], v[236:239], v[10:13]
	v_mfma_f32_16x16x32_bf16 v[54:57], v[170:173], v[186:189], 0
	v_mfma_f32_16x16x32_bf16 v[50:53], v[178:181], v[186:189], 0
	v_mfma_f32_16x16x32_bf16 v[38:41], v[170:173], v[194:197], 0
	v_mfma_f32_16x16x32_bf16 v[34:37], v[178:181], v[194:197], 0
	v_mfma_f32_16x16x32_bf16 v[22:25], v[170:173], v[202:205], 0
	v_mfma_f32_16x16x32_bf16 v[18:21], v[178:181], v[202:205], 0
	v_mfma_f32_16x16x32_bf16 v[6:9], v[170:173], v[220:223], 0
	v_mfma_f32_16x16x32_bf16 v[2:5], v[178:181], v[220:223], 0
	v_mfma_f32_16x16x32_bf16 v[54:57], v[174:177], v[190:193], v[54:57]
	v_mfma_f32_16x16x32_bf16 v[50:53], v[182:185], v[190:193], v[50:53]
	v_mfma_f32_16x16x32_bf16 v[38:41], v[174:177], v[198:201], v[38:41]
	v_mfma_f32_16x16x32_bf16 v[34:37], v[182:185], v[198:201], v[34:37]
	v_mfma_f32_16x16x32_bf16 v[22:25], v[174:177], v[206:209], v[22:25]
	v_mfma_f32_16x16x32_bf16 v[18:21], v[182:185], v[206:209], v[18:21]
	v_mfma_f32_16x16x32_bf16 v[6:9], v[174:177], v[236:239], v[6:9]
	v_mfma_f32_16x16x32_bf16 v[2:5], v[182:185], v[236:239], v[2:5]
	s_barrier
	s_add_i32 s56, 0, 0x18000
	s_add_i32 s57, 0, 0x1c000
	v_add_u32_e32 v166, s56, v147
	v_add_u32_e32 v182, s57, v147
	ds_read_b128 v[142:145], v166
	ds_read_b128 v[158:161], v166 offset:1024
	ds_read_b128 v[162:165], v166 offset:2048
	ds_read_b128 v[166:169], v166 offset:3072
	ds_read_b128 v[170:173], v182
	ds_read_b128 v[174:177], v182 offset:1024
	ds_read_b128 v[178:181], v182 offset:2048
	ds_read_b128 v[182:185], v182 offset:3072
	s_add_u32 s34, s34, 0x40000
	s_addc_u32 s35, s35, 0
	s_mov_b32 m0, s43
	v_lshl_add_u64 v[244:245], s[34:35], 0, v[130:131]
	ds_read_b128 v[186:189], v157 offset:32768
	ds_read_b128 v[190:193], v157 offset:33792
	ds_read_b128 v[194:197], v157 offset:34816
	ds_read_b128 v[198:201], v157 offset:35840
	ds_read_b128 v[202:205], v157 offset:36864
	ds_read_b128 v[206:209], v157 offset:37888
	ds_read_b128 v[220:223], v157 offset:38912
	ds_read_b128 v[236:239], v157 offset:39936
	global_load_lds_dwordx4 v[244:245], off
	v_lshl_add_u64 v[244:245], s[34:35], 0, v[134:135]
	s_mov_b32 m0, s46
	s_nop 0
	global_load_lds_dwordx4 v[244:245], off
	s_nop 0
	s_nop 0
	s_nop 0
	s_nop 0
	s_nop 0
	s_nop 0
	s_nop 0
	s_waitcnt vmcnt(8)
	s_waitcnt lgkmcnt(0)
	s_barrier
	s_waitcnt lgkmcnt(0)
	v_mfma_f32_16x16x32_bf16 v[126:129], v[142:145], v[186:189], v[126:129]
	v_mfma_f32_16x16x32_bf16 v[122:125], v[162:165], v[186:189], v[122:125]
	v_mfma_f32_16x16x32_bf16 v[110:113], v[142:145], v[194:197], v[110:113]
	v_mfma_f32_16x16x32_bf16 v[106:109], v[162:165], v[194:197], v[106:109]
	v_mfma_f32_16x16x32_bf16 v[94:97], v[142:145], v[202:205], v[94:97]
	v_mfma_f32_16x16x32_bf16 v[90:93], v[162:165], v[202:205], v[90:93]
	v_mfma_f32_16x16x32_bf16 v[78:81], v[142:145], v[220:223], v[78:81]
	v_mfma_f32_16x16x32_bf16 v[74:77], v[162:165], v[220:223], v[74:77]
	v_mfma_f32_16x16x32_bf16 v[126:129], v[158:161], v[190:193], v[126:129]
	v_mfma_f32_16x16x32_bf16 v[122:125], v[166:169], v[190:193], v[122:125]
	v_mfma_f32_16x16x32_bf16 v[110:113], v[158:161], v[198:201], v[110:113]
	v_mfma_f32_16x16x32_bf16 v[106:109], v[166:169], v[198:201], v[106:109]
	v_mfma_f32_16x16x32_bf16 v[94:97], v[158:161], v[206:209], v[94:97]
	v_mfma_f32_16x16x32_bf16 v[90:93], v[166:169], v[206:209], v[90:93]
	v_mfma_f32_16x16x32_bf16 v[78:81], v[158:161], v[236:239], v[78:81]
	v_mfma_f32_16x16x32_bf16 v[74:77], v[166:169], v[236:239], v[74:77]
	v_mfma_f32_16x16x32_bf16 v[118:121], v[170:173], v[186:189], v[118:121]
	v_mfma_f32_16x16x32_bf16 v[114:117], v[178:181], v[186:189], v[114:117]
	v_mfma_f32_16x16x32_bf16 v[102:105], v[170:173], v[194:197], v[102:105]
	v_mfma_f32_16x16x32_bf16 v[98:101], v[178:181], v[194:197], v[98:101]
	v_mfma_f32_16x16x32_bf16 v[86:89], v[170:173], v[202:205], v[86:89]
	v_mfma_f32_16x16x32_bf16 v[82:85], v[178:181], v[202:205], v[82:85]
	v_mfma_f32_16x16x32_bf16 v[70:73], v[170:173], v[220:223], v[70:73]
	v_mfma_f32_16x16x32_bf16 v[66:69], v[178:181], v[220:223], v[66:69]
	v_mfma_f32_16x16x32_bf16 v[118:121], v[174:177], v[190:193], v[118:121]
	v_mfma_f32_16x16x32_bf16 v[114:117], v[182:185], v[190:193], v[114:117]
	v_mfma_f32_16x16x32_bf16 v[102:105], v[174:177], v[198:201], v[102:105]
	v_mfma_f32_16x16x32_bf16 v[98:101], v[182:185], v[198:201], v[98:101]
	v_mfma_f32_16x16x32_bf16 v[86:89], v[174:177], v[206:209], v[86:89]
	v_mfma_f32_16x16x32_bf16 v[82:85], v[182:185], v[206:209], v[82:85]
	v_mfma_f32_16x16x32_bf16 v[70:73], v[174:177], v[236:239], v[70:73]
	v_mfma_f32_16x16x32_bf16 v[66:69], v[182:185], v[236:239], v[66:69]
	s_barrier
	s_add_i32 s34, s56, s27
	v_lshl_add_u64 v[224:225], v[224:225], 0, s[96:97]
	s_mov_b32 m0, s34
	ds_read_b128 v[186:189], v157 offset:49152
	ds_read_b128 v[190:193], v157 offset:50176
	ds_read_b128 v[194:197], v157 offset:51200
	ds_read_b128 v[198:201], v157 offset:52224
	ds_read_b128 v[202:205], v157 offset:53248
	ds_read_b128 v[206:209], v157 offset:54272
	ds_read_b128 v[220:223], v157 offset:55296
	ds_read_b128 v[236:239], v157 offset:56320
	global_load_lds_dwordx4 v[224:225], off
	s_add_i32 m0, s34, 0x2000
	s_add_u32 s30, s30, 0x40080
	v_lshl_add_u64 v[224:225], v[230:231], 0, s[96:97]
	s_addc_u32 s31, s31, 0
	s_add_i32 s34, s57, s27
	global_load_lds_dwordx4 v[224:225], off
	v_lshl_add_u64 v[224:225], s[30:31], 0, v[132:133]
	s_mov_b32 m0, s34
	s_nop 0
	global_load_lds_dwordx4 v[224:225], off
	v_lshl_add_u64 v[224:225], s[30:31], 0, v[136:137]
	s_add_i32 m0, s34, 0x2000
	s_nop 0
	global_load_lds_dwordx4 v[224:225], off
	v_lshl_add_u64 v[224:225], v[240:241], 0, s[96:97]
	s_mov_b32 m0, s47
	s_nop 0
	global_load_lds_dwordx4 v[224:225], off
	v_lshl_add_u64 v[224:225], v[242:243], 0, s[96:97]
	s_mov_b32 m0, s48
	s_nop 0
	global_load_lds_dwordx4 v[224:225], off
	s_nop 0
	s_nop 0
	s_waitcnt vmcnt(8)
	s_waitcnt lgkmcnt(0)
	s_barrier
	s_waitcnt lgkmcnt(0)
	v_mfma_f32_16x16x32_bf16 v[62:65], v[142:145], v[186:189], v[62:65]
	v_mfma_f32_16x16x32_bf16 v[58:61], v[162:165], v[186:189], v[58:61]
	v_mfma_f32_16x16x32_bf16 v[46:49], v[142:145], v[194:197], v[46:49]
	v_mfma_f32_16x16x32_bf16 v[42:45], v[162:165], v[194:197], v[42:45]
	v_mfma_f32_16x16x32_bf16 v[30:33], v[142:145], v[202:205], v[30:33]
	v_mfma_f32_16x16x32_bf16 v[26:29], v[162:165], v[202:205], v[26:29]
	v_mfma_f32_16x16x32_bf16 v[14:17], v[142:145], v[220:223], v[14:17]
	v_mfma_f32_16x16x32_bf16 v[10:13], v[162:165], v[220:223], v[10:13]
	v_mfma_f32_16x16x32_bf16 v[62:65], v[158:161], v[190:193], v[62:65]
	v_mfma_f32_16x16x32_bf16 v[58:61], v[166:169], v[190:193], v[58:61]
	v_mfma_f32_16x16x32_bf16 v[46:49], v[158:161], v[198:201], v[46:49]
	v_mfma_f32_16x16x32_bf16 v[42:45], v[166:169], v[198:201], v[42:45]
	v_mfma_f32_16x16x32_bf16 v[30:33], v[158:161], v[206:209], v[30:33]
	v_mfma_f32_16x16x32_bf16 v[26:29], v[166:169], v[206:209], v[26:29]
	v_mfma_f32_16x16x32_bf16 v[14:17], v[158:161], v[236:239], v[14:17]
	v_mfma_f32_16x16x32_bf16 v[10:13], v[166:169], v[236:239], v[10:13]
	v_mfma_f32_16x16x32_bf16 v[54:57], v[170:173], v[186:189], v[54:57]
	v_mfma_f32_16x16x32_bf16 v[50:53], v[178:181], v[186:189], v[50:53]
	v_mfma_f32_16x16x32_bf16 v[38:41], v[170:173], v[194:197], v[38:41]
	v_mfma_f32_16x16x32_bf16 v[34:37], v[178:181], v[194:197], v[34:37]
	v_mfma_f32_16x16x32_bf16 v[22:25], v[170:173], v[202:205], v[22:25]
	v_mfma_f32_16x16x32_bf16 v[18:21], v[178:181], v[202:205], v[18:21]
	v_mfma_f32_16x16x32_bf16 v[6:9], v[170:173], v[220:223], v[6:9]
	v_mfma_f32_16x16x32_bf16 v[2:5], v[178:181], v[220:223], v[2:5]
	v_mfma_f32_16x16x32_bf16 v[54:57], v[174:177], v[190:193], v[54:57]
	v_mfma_f32_16x16x32_bf16 v[50:53], v[182:185], v[190:193], v[50:53]
	v_mfma_f32_16x16x32_bf16 v[38:41], v[174:177], v[198:201], v[38:41]
	v_mfma_f32_16x16x32_bf16 v[34:37], v[182:185], v[198:201], v[34:37]
	v_mfma_f32_16x16x32_bf16 v[22:25], v[174:177], v[206:209], v[22:25]
	v_mfma_f32_16x16x32_bf16 v[18:21], v[182:185], v[206:209], v[18:21]
	v_mfma_f32_16x16x32_bf16 v[6:9], v[174:177], v[236:239], v[6:9]
	v_mfma_f32_16x16x32_bf16 v[2:5], v[182:185], v[236:239], v[2:5]
	s_barrier
	s_add_i32 s55, s55, 2
	s_add_u32 s38, s38, 0x100
	s_addc_u32 s39, s39, 0
	s_add_u32 s28, s28, 0x100
	s_addc_u32 s29, s29, 0
	s_cmp_gt_u32 s55, 13

.LBB0_360:
	s_add_i32 s55, s38, 1
	s_mul_i32 s6, s55, s54
	s_mul_hi_u32 s7, s55, s98
	s_add_i32 s7, s7, s6
	s_mul_i32 s6, s55, s98
	v_readlane_b32 s24, v254, 47
	v_readlane_b32 s25, v254, 48
	s_add_u32 s24, s6, s24
	s_addc_u32 s25, s7, s47
	v_mov_b64_e32 v[2:3], 0x580
	v_cmp_lt_i64_e64 s[6:7], s[24:25], v[2:3]
	v_mov_b64_e32 v[2:3], 0x57f
	v_cmp_gt_i64_e32 vcc, s[24:25], v[2:3]
	s_cbranch_vccnz .LBB0_362
	s_cmpk_lg_i32 s98, 0x100
	s_cbranch_scc1 .Lsw_dec_gen
	s_add_i32 s20, s29, 4
	s_mov_b32 s22, s28
	s_branch .LBB0_362
.Lsw_dec_gen:
	s_ashr_i32 s20, s24, 31
	s_lshr_b32 s20, s20, 29
	s_add_i32 s20, s24, s20
	s_ashr_i32 s21, s20, 3
	s_and_b32 s20, s20, -8
	s_sub_i32 s20, s24, s20
	s_cmp_lt_i32 s20, 0
	s_movk_i32 s22, 0xb1
	s_cselect_b32 s22, s22, 0xb0
	s_mul_i32 s20, s20, s22
	s_add_i32 s20, s20, s21
	s_mul_hi_i32 s21, s20, 0x2e8ba2e9
	s_lshr_b32 s22, s21, 31
	s_ashr_i32 s21, s21, 5
	s_add_i32 s21, s21, s22
	s_lshl_b32 s22, s21, 3
	s_sub_i32 s23, 64, s22
	s_min_i32 s23, s23, 8
	s_abs_i32 s24, s23
	v_cvt_f32_u32_e32 v2, s24
	s_sub_i32 s26, 0, s24
	s_mulk_i32 s21, 0xb0
	s_sub_i32 s21, s20, s21
	v_rcp_iflag_f32_e32 v2, v2
	s_abs_i32 s20, s21
	s_xor_b32 s25, s21, s23
	s_ashr_i32 s25, s25, 31
	v_mul_f32_e32 v2, 0x4f7ffffe, v2
	v_cvt_u32_f32_e32 v2, v2
	s_nop 0
	v_readfirstlane_b32 s27, v2
	s_mul_i32 s26, s26, s27
	s_mul_hi_u32 s26, s27, s26
	s_add_i32 s27, s27, s26
	s_mul_hi_u32 s26, s20, s27
	s_mul_i32 s27, s26, s24
	s_sub_i32 s20, s20, s27
	s_add_i32 s36, s26, 1
	s_sub_i32 s27, s20, s24
	s_cmp_ge_u32 s20, s24
	s_cselect_b32 s26, s36, s26
	s_cselect_b32 s20, s27, s20
	s_add_i32 s27, s26, 1
	s_cmp_ge_u32 s20, s24
	s_cselect_b32 s20, s27, s26
	s_xor_b32 s20, s20, s25
	s_sub_i32 s20, s20, s25
	s_mul_i32 s23, s20, s23
	s_sub_i32 s21, s21, s23
	s_add_i32 s22, s22, s21
.LBB0_362:
	s_ashr_i32 s23, s22, 31
	s_lshl_b64 s[24:25], s[22:23], 19
	s_add_u32 s24, s80, s24
	s_addc_u32 s25, s81, s25
	s_and_b64 s[26:27], s[6:7], exec
	s_cselect_b32 s23, s25, s35
	s_cselect_b32 s39, s24, s34
	s_ashr_i32 s21, s20, 31
	s_lshl_b64 s[26:27], s[20:21], 19
	s_add_u32 s26, s45, s26
	s_addc_u32 s27, s46, s27
	s_and_b64 s[36:37], s[6:7], exec
	s_cselect_b32 s21, s27, s31
	s_cselect_b32 s40, s26, s30
	s_add_u32 s41, s30, 0x100
	s_addc_u32 s43, s31, 0
	s_add_u32 s30, s34, 0x40080
	s_addc_u32 s31, s35, 0
	s_mov_b32 s56, -2
	s_add_u32 s34, s30, 0xfffc0080
	s_addc_u32 s35, s31, -1
	s_add_i32 s57, 0, 0x10000
	s_cmp_eq_u32 s56, 12
	s_cselect_b32 s37, s23, s35
	s_cselect_b32 s36, s39, s34
	v_add_u32_e32 v146, s57, v155
	s_cselect_b32 s35, s21, s43
	s_cselect_b32 s34, s40, s41
	s_add_i32 s60, 0, 0x14000
	ds_read_b128 v[142:145], v146
	ds_read_b128 v[168:171], v146 offset:1024
	ds_read_b128 v[172:175], v146 offset:2048
	ds_read_b128 v[176:179], v146 offset:3072
	v_add_u32_e32 v146, s60, v155
	ds_read_b128 v[180:183], v146
	ds_read_b128 v[184:187], v146 offset:1024
	ds_read_b128 v[188:191], v146 offset:2048
	ds_read_b128 v[192:195], v146 offset:3072
	v_lshl_add_u64 v[146:147], s[30:31], 0, v[140:141]
	s_add_i32 m0, s48, 0xc000
	ds_read_b128 v[196:199], v157
	ds_read_b128 v[200:203], v157 offset:1024
	ds_read_b128 v[204:207], v157 offset:2048
	ds_read_b128 v[220:223], v157 offset:3072
	ds_read_b128 v[236:239], v157 offset:4096
	ds_read_b128 v[240:243], v157 offset:5120
	ds_read_b128 v[244:247], v157 offset:6144
	ds_read_b128 v[248:251], v157 offset:7168
	global_load_lds_dwordx4 v[146:147], off
	v_lshl_add_u64 v[146:147], s[30:31], 0, v[138:139]
	s_add_i32 m0, s48, 0xe000
	s_nop 0
	global_load_lds_dwordx4 v[146:147], off
	s_nop 0
	s_nop 0
	s_nop 0
	s_nop 0
	s_nop 0
	s_nop 0
	s_nop 0
	s_nop 0
	s_nop 0
	s_nop 0
	s_nop 0
	s_nop 0
	s_nop 0
	s_nop 0
	s_nop 0
	s_nop 0
	s_nop 0
	s_nop 0
	s_nop 0
	s_nop 0
	s_nop 0
	s_waitcnt vmcnt(8)
	s_waitcnt lgkmcnt(0)
	s_barrier
	s_waitcnt lgkmcnt(0)
	v_mfma_f32_16x16x32_bf16 v[126:129], v[142:145], v[196:199], 0
	v_mfma_f32_16x16x32_bf16 v[118:121], v[172:175], v[196:199], 0
	v_mfma_f32_16x16x32_bf16 v[110:113], v[142:145], v[204:207], 0
	v_mfma_f32_16x16x32_bf16 v[102:105], v[172:175], v[204:207], 0
	v_mfma_f32_16x16x32_bf16 v[94:97], v[142:145], v[236:239], 0
	v_mfma_f32_16x16x32_bf16 v[86:89], v[172:175], v[236:239], 0
	v_mfma_f32_16x16x32_bf16 v[78:81], v[142:145], v[244:247], 0
	v_mfma_f32_16x16x32_bf16 v[70:73], v[172:175], v[244:247], 0
	v_mfma_f32_16x16x32_bf16 v[126:129], v[168:171], v[200:203], v[126:129]
	v_mfma_f32_16x16x32_bf16 v[118:121], v[176:179], v[200:203], v[118:121]
	v_mfma_f32_16x16x32_bf16 v[110:113], v[168:171], v[220:223], v[110:113]
	v_mfma_f32_16x16x32_bf16 v[102:105], v[176:179], v[220:223], v[102:105]
	v_mfma_f32_16x16x32_bf16 v[94:97], v[168:171], v[240:243], v[94:97]
	v_mfma_f32_16x16x32_bf16 v[86:89], v[176:179], v[240:243], v[86:89]
	v_mfma_f32_16x16x32_bf16 v[78:81], v[168:171], v[248:251], v[78:81]
	v_mfma_f32_16x16x32_bf16 v[70:73], v[176:179], v[248:251], v[70:73]
	v_mfma_f32_16x16x32_bf16 v[122:125], v[180:183], v[196:199], 0
	v_mfma_f32_16x16x32_bf16 v[114:117], v[188:191], v[196:199], 0
	v_mfma_f32_16x16x32_bf16 v[106:109], v[180:183], v[204:207], 0
	v_mfma_f32_16x16x32_bf16 v[98:101], v[188:191], v[204:207], 0
	v_mfma_f32_16x16x32_bf16 v[90:93], v[180:183], v[236:239], 0
	v_mfma_f32_16x16x32_bf16 v[82:85], v[188:191], v[236:239], 0
	v_mfma_f32_16x16x32_bf16 v[74:77], v[180:183], v[244:247], 0
	v_mfma_f32_16x16x32_bf16 v[66:69], v[188:191], v[244:247], 0
	v_mfma_f32_16x16x32_bf16 v[122:125], v[184:187], v[200:203], v[122:125]
	v_mfma_f32_16x16x32_bf16 v[114:117], v[192:195], v[200:203], v[114:117]
	v_mfma_f32_16x16x32_bf16 v[106:109], v[184:187], v[220:223], v[106:109]
	v_mfma_f32_16x16x32_bf16 v[98:101], v[192:195], v[220:223], v[98:101]
	v_mfma_f32_16x16x32_bf16 v[90:93], v[184:187], v[240:243], v[90:93]
	v_mfma_f32_16x16x32_bf16 v[82:85], v[192:195], v[240:243], v[82:85]
	v_mfma_f32_16x16x32_bf16 v[74:77], v[184:187], v[248:251], v[74:77]
	v_mfma_f32_16x16x32_bf16 v[66:69], v[192:195], v[248:251], v[66:69]
	s_barrier
	s_add_i32 s57, s57, s44
	v_lshl_add_u64 v[146:147], s[34:35], 0, v[134:135]
	s_mov_b32 m0, s57
	ds_read_b128 v[196:199], v157 offset:16384
	ds_read_b128 v[200:203], v157 offset:17408
	ds_read_b128 v[204:207], v157 offset:18432
	ds_read_b128 v[220:223], v157 offset:19456
	ds_read_b128 v[236:239], v157 offset:20480
	ds_read_b128 v[240:243], v157 offset:21504
	ds_read_b128 v[244:247], v157 offset:22528
	ds_read_b128 v[248:251], v157 offset:23552
	global_load_lds_dwordx4 v[146:147], off
	s_add_i32 m0, s57, 0x2000
	s_add_u32 s58, s34, 0x40000
	v_lshl_add_u64 v[208:209], s[34:35], 0, v[130:131]
	s_addc_u32 s59, s35, 0
	s_add_i32 s57, s60, s44
	global_load_lds_dwordx4 v[208:209], off
	v_lshl_add_u64 v[224:225], s[58:59], 0, v[134:135]
	s_mov_b32 m0, s57
	v_lshl_add_u64 v[230:231], s[36:37], 0, v[132:133]
	global_load_lds_dwordx4 v[224:225], off
	v_lshl_add_u64 v[224:225], s[58:59], 0, v[130:131]
	s_add_i32 m0, s57, 0x2000
	s_nop 0
	global_load_lds_dwordx4 v[224:225], off
	v_lshl_add_u64 v[224:225], s[36:37], 0, v[136:137]
	s_mov_b32 m0, s48
	s_nop 0
	global_load_lds_dwordx4 v[224:225], off
	s_mov_b32 m0, s49
	s_nop 0
	global_load_lds_dwordx4 v[230:231], off
	s_nop 0
	s_nop 0
	s_nop 0
	s_waitcnt vmcnt(8)
	s_waitcnt lgkmcnt(0)
	s_barrier
	s_waitcnt lgkmcnt(0)
	v_mfma_f32_16x16x32_bf16 v[62:65], v[142:145], v[196:199], 0
	v_mfma_f32_16x16x32_bf16 v[54:57], v[172:175], v[196:199], 0
	v_mfma_f32_16x16x32_bf16 v[46:49], v[142:145], v[204:207], 0
	v_mfma_f32_16x16x32_bf16 v[38:41], v[172:175], v[204:207], 0
	v_mfma_f32_16x16x32_bf16 v[30:33], v[142:145], v[236:239], 0
	v_mfma_f32_16x16x32_bf16 v[22:25], v[172:175], v[236:239], 0
	v_mfma_f32_16x16x32_bf16 v[14:17], v[142:145], v[244:247], 0
	v_mfma_f32_16x16x32_bf16 v[6:9], v[172:175], v[244:247], 0
	v_mfma_f32_16x16x32_bf16 v[62:65], v[168:171], v[200:203], v[62:65]
	v_mfma_f32_16x16x32_bf16 v[54:57], v[176:179], v[200:203], v[54:57]
	v_mfma_f32_16x16x32_bf16 v[46:49], v[168:171], v[220:223], v[46:49]
	v_mfma_f32_16x16x32_bf16 v[38:41], v[176:179], v[220:223], v[38:41]
	v_mfma_f32_16x16x32_bf16 v[30:33], v[168:171], v[240:243], v[30:33]
	v_mfma_f32_16x16x32_bf16 v[22:25], v[176:179], v[240:243], v[22:25]
	v_mfma_f32_16x16x32_bf16 v[14:17], v[168:171], v[248:251], v[14:17]
	v_mfma_f32_16x16x32_bf16 v[6:9], v[176:179], v[248:251], v[6:9]
	v_mfma_f32_16x16x32_bf16 v[58:61], v[180:183], v[196:199], 0
	v_mfma_f32_16x16x32_bf16 v[50:53], v[188:191], v[196:199], 0
	v_mfma_f32_16x16x32_bf16 v[42:45], v[180:183], v[204:207], 0
	v_mfma_f32_16x16x32_bf16 v[34:37], v[188:191], v[204:207], 0
	v_mfma_f32_16x16x32_bf16 v[26:29], v[180:183], v[236:239], 0
	v_mfma_f32_16x16x32_bf16 v[18:21], v[188:191], v[236:239], 0
	v_mfma_f32_16x16x32_bf16 v[10:13], v[180:183], v[244:247], 0
	v_mfma_f32_16x16x32_bf16 v[2:5], v[188:191], v[244:247], 0
	v_mfma_f32_16x16x32_bf16 v[58:61], v[184:187], v[200:203], v[58:61]
	v_mfma_f32_16x16x32_bf16 v[50:53], v[192:195], v[200:203], v[50:53]
	v_mfma_f32_16x16x32_bf16 v[42:45], v[184:187], v[220:223], v[42:45]
	v_mfma_f32_16x16x32_bf16 v[34:37], v[192:195], v[220:223], v[34:37]
	v_mfma_f32_16x16x32_bf16 v[26:29], v[184:187], v[240:243], v[26:29]
	v_mfma_f32_16x16x32_bf16 v[18:21], v[192:195], v[240:243], v[18:21]
	v_mfma_f32_16x16x32_bf16 v[10:13], v[184:187], v[248:251], v[10:13]
	v_mfma_f32_16x16x32_bf16 v[2:5], v[192:195], v[248:251], v[2:5]
	s_barrier
	s_add_i32 s57, 0, 0x18000
	v_add_u32_e32 v164, s57, v155
	s_add_i32 s58, 0, 0x1c000
	ds_read_b128 v[142:145], v164
	ds_read_b128 v[168:171], v164 offset:1024
	ds_read_b128 v[172:175], v164 offset:2048
	ds_read_b128 v[176:179], v164 offset:3072
	v_add_u32_e32 v164, s58, v155
	ds_read_b128 v[180:183], v164
	ds_read_b128 v[184:187], v164 offset:1024
	ds_read_b128 v[188:191], v164 offset:2048
	ds_read_b128 v[192:195], v164 offset:3072
	s_add_u32 s36, s36, 0x40000
	s_addc_u32 s37, s37, 0
	s_mov_b32 m0, s50
	v_lshl_add_u64 v[252:253], s[36:37], 0, v[136:137]
	ds_read_b128 v[196:199], v157 offset:32768
	ds_read_b128 v[200:203], v157 offset:33792
	ds_read_b128 v[204:207], v157 offset:34816
	ds_read_b128 v[220:223], v157 offset:35840
	ds_read_b128 v[236:239], v157 offset:36864
	ds_read_b128 v[240:243], v157 offset:37888
	ds_read_b128 v[244:247], v157 offset:38912
	ds_read_b128 v[248:251], v157 offset:39936
	global_load_lds_dwordx4 v[252:253], off
	v_lshl_add_u64 v[252:253], s[36:37], 0, v[132:133]
	s_mov_b32 m0, s51
	s_nop 0
	global_load_lds_dwordx4 v[252:253], off
	s_nop 0
	s_nop 0
	s_nop 0
	s_nop 0
	s_nop 0
	s_nop 0
	s_nop 0
	s_waitcnt vmcnt(8)
	s_waitcnt lgkmcnt(0)
	s_barrier
	s_waitcnt lgkmcnt(0)
	v_mfma_f32_16x16x32_bf16 v[126:129], v[142:145], v[196:199], v[126:129]
	v_mfma_f32_16x16x32_bf16 v[118:121], v[172:175], v[196:199], v[118:121]
	v_mfma_f32_16x16x32_bf16 v[110:113], v[142:145], v[204:207], v[110:113]
	v_mfma_f32_16x16x32_bf16 v[102:105], v[172:175], v[204:207], v[102:105]
	v_mfma_f32_16x16x32_bf16 v[94:97], v[142:145], v[236:239], v[94:97]
	v_mfma_f32_16x16x32_bf16 v[86:89], v[172:175], v[236:239], v[86:89]
	v_mfma_f32_16x16x32_bf16 v[78:81], v[142:145], v[244:247], v[78:81]
	v_mfma_f32_16x16x32_bf16 v[70:73], v[172:175], v[244:247], v[70:73]
	v_mfma_f32_16x16x32_bf16 v[126:129], v[168:171], v[200:203], v[126:129]
	v_mfma_f32_16x16x32_bf16 v[118:121], v[176:179], v[200:203], v[118:121]
	v_mfma_f32_16x16x32_bf16 v[110:113], v[168:171], v[220:223], v[110:113]
	v_mfma_f32_16x16x32_bf16 v[102:105], v[176:179], v[220:223], v[102:105]
	v_mfma_f32_16x16x32_bf16 v[94:97], v[168:171], v[240:243], v[94:97]
	v_mfma_f32_16x16x32_bf16 v[86:89], v[176:179], v[240:243], v[86:89]
	v_mfma_f32_16x16x32_bf16 v[78:81], v[168:171], v[248:251], v[78:81]
	v_mfma_f32_16x16x32_bf16 v[70:73], v[176:179], v[248:251], v[70:73]
	v_mfma_f32_16x16x32_bf16 v[122:125], v[180:183], v[196:199], v[122:125]
	v_mfma_f32_16x16x32_bf16 v[114:117], v[188:191], v[196:199], v[114:117]
	v_mfma_f32_16x16x32_bf16 v[106:109], v[180:183], v[204:207], v[106:109]
	v_mfma_f32_16x16x32_bf16 v[98:101], v[188:191], v[204:207], v[98:101]
	v_mfma_f32_16x16x32_bf16 v[90:93], v[180:183], v[236:239], v[90:93]
	v_mfma_f32_16x16x32_bf16 v[82:85], v[188:191], v[236:239], v[82:85]
	v_mfma_f32_16x16x32_bf16 v[74:77], v[180:183], v[244:247], v[74:77]
	v_mfma_f32_16x16x32_bf16 v[66:69], v[188:191], v[244:247], v[66:69]
	v_mfma_f32_16x16x32_bf16 v[122:125], v[184:187], v[200:203], v[122:125]
	v_mfma_f32_16x16x32_bf16 v[114:117], v[192:195], v[200:203], v[114:117]
	v_mfma_f32_16x16x32_bf16 v[106:109], v[184:187], v[220:223], v[106:109]
	v_mfma_f32_16x16x32_bf16 v[98:101], v[192:195], v[220:223], v[98:101]
	v_mfma_f32_16x16x32_bf16 v[90:93], v[184:187], v[240:243], v[90:93]
	v_mfma_f32_16x16x32_bf16 v[82:85], v[192:195], v[240:243], v[82:85]
	v_mfma_f32_16x16x32_bf16 v[74:77], v[184:187], v[248:251], v[74:77]
	v_mfma_f32_16x16x32_bf16 v[66:69], v[192:195], v[248:251], v[66:69]
	s_barrier
	s_add_i32 s36, s57, s44
	v_lshl_add_u64 v[146:147], v[146:147], 0, s[96:97]
	s_mov_b32 m0, s36
	ds_read_b128 v[196:199], v157 offset:49152
	ds_read_b128 v[200:203], v157 offset:50176
	ds_read_b128 v[204:207], v157 offset:51200
	ds_read_b128 v[220:223], v157 offset:52224
	ds_read_b128 v[236:239], v157 offset:53248
	ds_read_b128 v[240:243], v157 offset:54272
	ds_read_b128 v[244:247], v157 offset:55296
	ds_read_b128 v[248:251], v157 offset:56320
	global_load_lds_dwordx4 v[146:147], off
	s_add_i32 m0, s36, 0x2000
	s_add_u32 s34, s34, 0x40080
	v_lshl_add_u64 v[146:147], v[208:209], 0, s[96:97]
	s_addc_u32 s35, s35, 0
	s_add_i32 s36, s58, s44
	global_load_lds_dwordx4 v[146:147], off
	v_lshl_add_u64 v[146:147], s[34:35], 0, v[134:135]
	s_mov_b32 m0, s36
	s_nop 0
	global_load_lds_dwordx4 v[146:147], off
	v_lshl_add_u64 v[146:147], s[34:35], 0, v[130:131]
	s_add_i32 m0, s36, 0x2000
	s_nop 0
	global_load_lds_dwordx4 v[146:147], off
	v_lshl_add_u64 v[146:147], v[224:225], 0, s[96:97]
	s_mov_b32 m0, s52
	s_nop 0
	global_load_lds_dwordx4 v[146:147], off
	v_lshl_add_u64 v[146:147], v[230:231], 0, s[96:97]
	s_mov_b32 m0, s53
	s_nop 0
	global_load_lds_dwordx4 v[146:147], off
	s_nop 0
	s_nop 0
	s_waitcnt vmcnt(8)
	s_waitcnt lgkmcnt(0)
	s_barrier
	s_waitcnt lgkmcnt(0)
	v_mfma_f32_16x16x32_bf16 v[62:65], v[142:145], v[196:199], v[62:65]
	v_mfma_f32_16x16x32_bf16 v[54:57], v[172:175], v[196:199], v[54:57]
	v_mfma_f32_16x16x32_bf16 v[46:49], v[142:145], v[204:207], v[46:49]
	v_mfma_f32_16x16x32_bf16 v[38:41], v[172:175], v[204:207], v[38:41]
	v_mfma_f32_16x16x32_bf16 v[30:33], v[142:145], v[236:239], v[30:33]
	v_mfma_f32_16x16x32_bf16 v[22:25], v[172:175], v[236:239], v[22:25]
	v_mfma_f32_16x16x32_bf16 v[14:17], v[142:145], v[244:247], v[14:17]
	v_mfma_f32_16x16x32_bf16 v[6:9], v[172:175], v[244:247], v[6:9]
	v_mfma_f32_16x16x32_bf16 v[62:65], v[168:171], v[200:203], v[62:65]
	v_mfma_f32_16x16x32_bf16 v[54:57], v[176:179], v[200:203], v[54:57]
	v_mfma_f32_16x16x32_bf16 v[46:49], v[168:171], v[220:223], v[46:49]
	v_mfma_f32_16x16x32_bf16 v[38:41], v[176:179], v[220:223], v[38:41]
	v_mfma_f32_16x16x32_bf16 v[30:33], v[168:171], v[240:243], v[30:33]
	v_mfma_f32_16x16x32_bf16 v[22:25], v[176:179], v[240:243], v[22:25]
	v_mfma_f32_16x16x32_bf16 v[14:17], v[168:171], v[248:251], v[14:17]
	v_mfma_f32_16x16x32_bf16 v[6:9], v[176:179], v[248:251], v[6:9]
	v_mfma_f32_16x16x32_bf16 v[58:61], v[180:183], v[196:199], v[58:61]
	v_mfma_f32_16x16x32_bf16 v[50:53], v[188:191], v[196:199], v[50:53]
	v_mfma_f32_16x16x32_bf16 v[42:45], v[180:183], v[204:207], v[42:45]
	v_mfma_f32_16x16x32_bf16 v[34:37], v[188:191], v[204:207], v[34:37]
	v_mfma_f32_16x16x32_bf16 v[26:29], v[180:183], v[236:239], v[26:29]
	v_mfma_f32_16x16x32_bf16 v[18:21], v[188:191], v[236:239], v[18:21]
	v_mfma_f32_16x16x32_bf16 v[10:13], v[180:183], v[244:247], v[10:13]
	v_mfma_f32_16x16x32_bf16 v[2:5], v[188:191], v[244:247], v[2:5]
	v_mfma_f32_16x16x32_bf16 v[58:61], v[184:187], v[200:203], v[58:61]
	v_mfma_f32_16x16x32_bf16 v[50:53], v[192:195], v[200:203], v[50:53]
	v_mfma_f32_16x16x32_bf16 v[42:45], v[184:187], v[220:223], v[42:45]
	v_mfma_f32_16x16x32_bf16 v[34:37], v[192:195], v[220:223], v[34:37]
	v_mfma_f32_16x16x32_bf16 v[26:29], v[184:187], v[240:243], v[26:29]
	v_mfma_f32_16x16x32_bf16 v[18:21], v[192:195], v[240:243], v[18:21]
	v_mfma_f32_16x16x32_bf16 v[10:13], v[184:187], v[248:251], v[10:13]
	v_mfma_f32_16x16x32_bf16 v[2:5], v[192:195], v[248:251], v[2:5]
	s_barrier
	s_add_i32 s56, s56, 2
	s_add_u32 s41, s41, 0x100
	s_addc_u32 s43, s43, 0
	s_add_u32 s30, s30, 0x100
	s_addc_u32 s31, s31, 0
	s_cmp_gt_u32 s56, 13

.LBB0_637:
	s_add_i32 s39, s39, 1
	s_mul_i32 s4, s39, s38
	s_mul_hi_u32 s5, s39, s98
	s_add_i32 s5, s5, s4
	s_mul_i32 s4, s39, s98
	s_add_u32 s14, s4, s52
	s_addc_u32 s15, s5, s29
	v_cmp_gt_i64_e32 vcc, s[14:15], v[212:213]
	v_cmp_lt_i64_e64 s[4:5], s[14:15], v[210:211]
	s_cbranch_vccnz .LBB0_639
	s_cmpk_lg_i32 s98, 0x100
	s_cbranch_scc1 .Lci_dec_gen
	s_add_i32 s10, s40, 4
	s_mov_b32 s12, s18
	s_branch .LBB0_639
.Lci_dec_gen:
	s_ashr_i32 s10, s14, 31
	s_lshr_b32 s10, s10, 29
	s_add_i32 s10, s14, s10
	s_ashr_i32 s11, s10, 3
	s_and_b32 s10, s10, -8
	s_sub_i32 s10, s14, s10
	s_cmp_lt_i32 s10, 0
	s_cselect_b32 s12, s49, 0x60
	s_mul_i32 s10, s10, s12
	s_add_i32 s10, s10, s11
	s_mul_hi_i32 s11, s10, 0x2aaaaaab
	s_lshr_b32 s12, s11, 31
	s_ashr_i32 s11, s11, 4
	s_add_i32 s11, s11, s12
	s_lshl_b32 s12, s11, 3
	s_sub_i32 s13, 64, s12
	s_min_i32 s13, s13, 8
	s_abs_i32 s14, s13
	v_cvt_f32_u32_e32 v2, s14
	s_sub_i32 s16, 0, s14
	s_mulk_i32 s11, 0x60
	s_sub_i32 s11, s10, s11
	v_rcp_iflag_f32_e32 v2, v2
	s_abs_i32 s10, s11
	s_xor_b32 s15, s11, s13
	s_ashr_i32 s15, s15, 31
	v_mul_f32_e32 v2, 0x4f7ffffe, v2
	v_cvt_u32_f32_e32 v2, v2
	s_nop 0
	v_readfirstlane_b32 s17, v2
	s_mul_i32 s16, s16, s17
	s_mul_hi_u32 s16, s17, s16
	s_add_i32 s17, s17, s16
	s_mul_hi_u32 s16, s10, s17
	s_mul_i32 s17, s16, s14
	s_sub_i32 s10, s10, s17
	s_add_i32 s19, s16, 1
	s_sub_i32 s17, s10, s14
	s_cmp_ge_u32 s10, s14
	s_cselect_b32 s16, s19, s16
	s_cselect_b32 s10, s17, s10
	s_add_i32 s17, s16, 1
	s_cmp_ge_u32 s10, s14
	s_cselect_b32 s10, s17, s16
	s_xor_b32 s10, s10, s15
	s_sub_i32 s10, s10, s15
	s_mul_i32 s13, s10, s13
	s_sub_i32 s11, s11, s13
	s_add_i32 s12, s12, s11
.LBB0_639:
	s_ashr_i32 s13, s12, 31
	s_lshl_b64 s[14:15], s[12:13], 19
	s_add_u32 s14, s80, s14
	s_addc_u32 s15, s81, s15
	s_and_b64 s[16:17], s[4:5], exec
	s_cselect_b32 s13, s15, s23
	s_cselect_b32 s19, s14, s22
	s_ashr_i32 s11, s10, 31
	s_lshl_b64 s[16:17], s[10:11], 19
	s_add_u32 s16, s26, s16
	s_addc_u32 s17, s27, s17
	s_and_b64 s[24:25], s[4:5], exec
	s_cselect_b32 s11, s17, s21
	s_cselect_b32 s41, s16, s20
	s_add_u32 s43, s20, 0x100
	s_addc_u32 s44, s21, 0
	s_add_u32 s20, s22, 0x40080
	s_addc_u32 s21, s23, 0
	s_mov_b32 s45, -2
	s_add_u32 s22, s20, 0xfffc0080
	s_addc_u32 s23, s21, -1
	s_add_i32 s46, 0, 0x10000
	s_cmp_eq_u32 s45, 12
	s_cselect_b32 s25, s13, s23
	s_cselect_b32 s24, s19, s22
	v_add_u32_e32 v150, s46, v159
	s_cselect_b32 s23, s11, s44
	s_cselect_b32 s22, s41, s43
	s_add_i32 s48, 0, 0x14000
	ds_read_b128 v[164:167], v150
	ds_read_b128 v[168:171], v150 offset:1024
	ds_read_b128 v[172:175], v150 offset:2048
	ds_read_b128 v[176:179], v150 offset:3072
	v_add_u32_e32 v150, s48, v159
	ds_read_b128 v[180:183], v150
	ds_read_b128 v[184:187], v150 offset:1024
	ds_read_b128 v[188:191], v150 offset:2048
	ds_read_b128 v[192:195], v150 offset:3072
	v_lshl_add_u64 v[150:151], s[20:21], 0, v[140:141]
	s_add_i32 m0, s30, 0xc000
	ds_read_b128 v[196:199], v162
	ds_read_b128 v[200:203], v162 offset:1024
	ds_read_b128 v[204:207], v162 offset:2048
	ds_read_b128 v[220:223], v162 offset:3072
	ds_read_b128 v[236:239], v162 offset:4096
	ds_read_b128 v[240:243], v162 offset:5120
	ds_read_b128 v[244:247], v162 offset:6144
	ds_read_b128 v[248:251], v162 offset:7168
	global_load_lds_dwordx4 v[150:151], off
	v_lshl_add_u64 v[150:151], s[20:21], 0, v[138:139]
	s_add_i32 m0, s30, 0xe000
	s_nop 0
	global_load_lds_dwordx4 v[150:151], off
	s_nop 0
	s_nop 0
	s_nop 0
	s_nop 0
	s_nop 0
	s_nop 0
	s_nop 0
	s_nop 0
	s_nop 0
	s_nop 0
	s_nop 0
	s_nop 0
	s_nop 0
	s_nop 0
	s_nop 0
	s_nop 0
	s_nop 0
	s_nop 0
	s_nop 0
	s_nop 0
	s_nop 0
	s_nop 0
	s_nop 0
	s_nop 0
	s_waitcnt vmcnt(8)
	s_waitcnt lgkmcnt(0)
	s_barrier
	s_waitcnt lgkmcnt(0)
	v_mfma_f32_16x16x32_bf16 v[126:129], v[164:167], v[196:199], 0
	v_mfma_f32_16x16x32_bf16 v[122:125], v[172:175], v[196:199], 0
	v_mfma_f32_16x16x32_bf16 v[118:121], v[164:167], v[204:207], 0
	v_mfma_f32_16x16x32_bf16 v[114:117], v[172:175], v[204:207], 0
	v_mfma_f32_16x16x32_bf16 v[110:113], v[164:167], v[236:239], 0
	v_mfma_f32_16x16x32_bf16 v[106:109], v[172:175], v[236:239], 0
	v_mfma_f32_16x16x32_bf16 v[102:105], v[164:167], v[244:247], 0
	v_mfma_f32_16x16x32_bf16 v[98:101], v[172:175], v[244:247], 0
	v_mfma_f32_16x16x32_bf16 v[126:129], v[168:171], v[200:203], v[126:129]
	v_mfma_f32_16x16x32_bf16 v[122:125], v[176:179], v[200:203], v[122:125]
	v_mfma_f32_16x16x32_bf16 v[118:121], v[168:171], v[220:223], v[118:121]
	v_mfma_f32_16x16x32_bf16 v[114:117], v[176:179], v[220:223], v[114:117]
	v_mfma_f32_16x16x32_bf16 v[110:113], v[168:171], v[240:243], v[110:113]
	v_mfma_f32_16x16x32_bf16 v[106:109], v[176:179], v[240:243], v[106:109]
	v_mfma_f32_16x16x32_bf16 v[102:105], v[168:171], v[248:251], v[102:105]
	v_mfma_f32_16x16x32_bf16 v[98:101], v[176:179], v[248:251], v[98:101]
	v_mfma_f32_16x16x32_bf16 v[94:97], v[180:183], v[196:199], 0
	v_mfma_f32_16x16x32_bf16 v[90:93], v[188:191], v[196:199], 0
	v_mfma_f32_16x16x32_bf16 v[86:89], v[180:183], v[204:207], 0
	v_mfma_f32_16x16x32_bf16 v[82:85], v[188:191], v[204:207], 0
	v_mfma_f32_16x16x32_bf16 v[78:81], v[180:183], v[236:239], 0
	v_mfma_f32_16x16x32_bf16 v[74:77], v[188:191], v[236:239], 0
	v_mfma_f32_16x16x32_bf16 v[70:73], v[180:183], v[244:247], 0
	v_mfma_f32_16x16x32_bf16 v[66:69], v[188:191], v[244:247], 0
	v_mfma_f32_16x16x32_bf16 v[94:97], v[184:187], v[200:203], v[94:97]
	v_mfma_f32_16x16x32_bf16 v[90:93], v[192:195], v[200:203], v[90:93]
	v_mfma_f32_16x16x32_bf16 v[86:89], v[184:187], v[220:223], v[86:89]
	v_mfma_f32_16x16x32_bf16 v[82:85], v[192:195], v[220:223], v[82:85]
	v_mfma_f32_16x16x32_bf16 v[78:81], v[184:187], v[240:243], v[78:81]
	v_mfma_f32_16x16x32_bf16 v[74:77], v[192:195], v[240:243], v[74:77]
	v_mfma_f32_16x16x32_bf16 v[70:73], v[184:187], v[248:251], v[70:73]
	v_mfma_f32_16x16x32_bf16 v[66:69], v[192:195], v[248:251], v[66:69]
	s_barrier
	s_add_i32 s46, s46, s28
	v_lshl_add_u64 v[150:151], s[22:23], 0, v[134:135]
	s_mov_b32 m0, s46
	ds_read_b128 v[196:199], v162 offset:16384
	ds_read_b128 v[200:203], v162 offset:17408
	ds_read_b128 v[204:207], v162 offset:18432
	ds_read_b128 v[220:223], v162 offset:19456
	ds_read_b128 v[236:239], v162 offset:20480
	ds_read_b128 v[240:243], v162 offset:21504
	ds_read_b128 v[244:247], v162 offset:22528
	ds_read_b128 v[248:251], v162 offset:23552
	global_load_lds_dwordx4 v[150:151], off
	s_add_i32 m0, s46, 0x2000
	s_add_u32 s46, s22, 0x40000
	v_lshl_add_u64 v[208:209], s[22:23], 0, v[130:131]
	s_addc_u32 s47, s23, 0
	s_add_i32 s48, s48, s28
	global_load_lds_dwordx4 v[208:209], off
	v_lshl_add_u64 v[224:225], s[46:47], 0, v[134:135]
	s_mov_b32 m0, s48
	v_lshl_add_u64 v[252:253], s[24:25], 0, v[132:133]
	global_load_lds_dwordx4 v[224:225], off
	v_lshl_add_u64 v[224:225], s[46:47], 0, v[130:131]
	s_add_i32 m0, s48, 0x2000
	s_nop 0
	global_load_lds_dwordx4 v[224:225], off
	v_lshl_add_u64 v[224:225], s[24:25], 0, v[136:137]
	s_mov_b32 m0, s30
	s_nop 0
	global_load_lds_dwordx4 v[224:225], off
	s_mov_b32 m0, s31
	s_nop 0
	global_load_lds_dwordx4 v[252:253], off
	s_nop 0
	s_nop 0
	s_nop 0
	s_waitcnt vmcnt(8)
	s_waitcnt lgkmcnt(0)
	s_barrier
	s_waitcnt lgkmcnt(0)
	v_mfma_f32_16x16x32_bf16 v[62:65], v[164:167], v[196:199], 0
	v_mfma_f32_16x16x32_bf16 v[58:61], v[172:175], v[196:199], 0
	v_mfma_f32_16x16x32_bf16 v[54:57], v[164:167], v[204:207], 0
	v_mfma_f32_16x16x32_bf16 v[50:53], v[172:175], v[204:207], 0
	v_mfma_f32_16x16x32_bf16 v[46:49], v[164:167], v[236:239], 0
	v_mfma_f32_16x16x32_bf16 v[42:45], v[172:175], v[236:239], 0
	v_mfma_f32_16x16x32_bf16 v[38:41], v[164:167], v[244:247], 0
	v_mfma_f32_16x16x32_bf16 v[34:37], v[172:175], v[244:247], 0
	v_mfma_f32_16x16x32_bf16 v[62:65], v[168:171], v[200:203], v[62:65]
	v_mfma_f32_16x16x32_bf16 v[58:61], v[176:179], v[200:203], v[58:61]
	v_mfma_f32_16x16x32_bf16 v[54:57], v[168:171], v[220:223], v[54:57]
	v_mfma_f32_16x16x32_bf16 v[50:53], v[176:179], v[220:223], v[50:53]
	v_mfma_f32_16x16x32_bf16 v[46:49], v[168:171], v[240:243], v[46:49]
	v_mfma_f32_16x16x32_bf16 v[42:45], v[176:179], v[240:243], v[42:45]
	v_mfma_f32_16x16x32_bf16 v[38:41], v[168:171], v[248:251], v[38:41]
	v_mfma_f32_16x16x32_bf16 v[34:37], v[176:179], v[248:251], v[34:37]
	v_mfma_f32_16x16x32_bf16 v[30:33], v[180:183], v[196:199], 0
	v_mfma_f32_16x16x32_bf16 v[26:29], v[188:191], v[196:199], 0
	v_mfma_f32_16x16x32_bf16 v[22:25], v[180:183], v[204:207], 0
	v_mfma_f32_16x16x32_bf16 v[18:21], v[188:191], v[204:207], 0
	v_mfma_f32_16x16x32_bf16 v[14:17], v[180:183], v[236:239], 0
	v_mfma_f32_16x16x32_bf16 v[10:13], v[188:191], v[236:239], 0
	v_mfma_f32_16x16x32_bf16 v[6:9], v[180:183], v[244:247], 0
	v_mfma_f32_16x16x32_bf16 v[2:5], v[188:191], v[244:247], 0
	v_mfma_f32_16x16x32_bf16 v[30:33], v[184:187], v[200:203], v[30:33]
	v_mfma_f32_16x16x32_bf16 v[26:29], v[192:195], v[200:203], v[26:29]
	v_mfma_f32_16x16x32_bf16 v[22:25], v[184:187], v[220:223], v[22:25]
	v_mfma_f32_16x16x32_bf16 v[18:21], v[192:195], v[220:223], v[18:21]
	v_mfma_f32_16x16x32_bf16 v[14:17], v[184:187], v[240:243], v[14:17]
	v_mfma_f32_16x16x32_bf16 v[10:13], v[192:195], v[240:243], v[10:13]
	v_mfma_f32_16x16x32_bf16 v[6:9], v[184:187], v[248:251], v[6:9]
	v_mfma_f32_16x16x32_bf16 v[2:5], v[192:195], v[248:251], v[2:5]
	s_barrier
	s_add_i32 s46, 0, 0x18000
	v_add_u32_e32 v163, s46, v159
	s_add_i32 s47, 0, 0x1c000
	ds_read_b128 v[164:167], v163
	ds_read_b128 v[168:171], v163 offset:1024
	ds_read_b128 v[172:175], v163 offset:2048
	ds_read_b128 v[176:179], v163 offset:3072
	v_add_u32_e32 v163, s47, v159
	ds_read_b128 v[180:183], v163
	ds_read_b128 v[184:187], v163 offset:1024
	ds_read_b128 v[188:191], v163 offset:2048
	ds_read_b128 v[192:195], v163 offset:3072
	s_add_u32 s24, s24, 0x40000
	s_addc_u32 s25, s25, 0
	s_mov_b32 m0, s34
	v_lshl_add_u64 v[230:231], s[24:25], 0, v[136:137]
	ds_read_b128 v[196:199], v162 offset:32768
	ds_read_b128 v[200:203], v162 offset:33792
	ds_read_b128 v[204:207], v162 offset:34816
	ds_read_b128 v[220:223], v162 offset:35840
	ds_read_b128 v[236:239], v162 offset:36864
	ds_read_b128 v[240:243], v162 offset:37888
	ds_read_b128 v[244:247], v162 offset:38912
	ds_read_b128 v[248:251], v162 offset:39936
	global_load_lds_dwordx4 v[230:231], off
	v_lshl_add_u64 v[230:231], s[24:25], 0, v[132:133]
	s_mov_b32 m0, s35
	s_nop 0
	global_load_lds_dwordx4 v[230:231], off
	s_nop 0
	s_nop 0
	s_nop 0
	s_nop 0
	s_nop 0
	s_nop 0
	s_nop 0
	s_waitcnt vmcnt(8)
	s_waitcnt lgkmcnt(0)
	s_barrier
	s_waitcnt lgkmcnt(0)
	v_mfma_f32_16x16x32_bf16 v[126:129], v[164:167], v[196:199], v[126:129]
	v_mfma_f32_16x16x32_bf16 v[122:125], v[172:175], v[196:199], v[122:125]
	v_mfma_f32_16x16x32_bf16 v[118:121], v[164:167], v[204:207], v[118:121]
	v_mfma_f32_16x16x32_bf16 v[114:117], v[172:175], v[204:207], v[114:117]
	v_mfma_f32_16x16x32_bf16 v[110:113], v[164:167], v[236:239], v[110:113]
	v_mfma_f32_16x16x32_bf16 v[106:109], v[172:175], v[236:239], v[106:109]
	v_mfma_f32_16x16x32_bf16 v[102:105], v[164:167], v[244:247], v[102:105]
	v_mfma_f32_16x16x32_bf16 v[98:101], v[172:175], v[244:247], v[98:101]
	v_mfma_f32_16x16x32_bf16 v[126:129], v[168:171], v[200:203], v[126:129]
	v_mfma_f32_16x16x32_bf16 v[122:125], v[176:179], v[200:203], v[122:125]
	v_mfma_f32_16x16x32_bf16 v[118:121], v[168:171], v[220:223], v[118:121]
	v_mfma_f32_16x16x32_bf16 v[114:117], v[176:179], v[220:223], v[114:117]
	v_mfma_f32_16x16x32_bf16 v[110:113], v[168:171], v[240:243], v[110:113]
	v_mfma_f32_16x16x32_bf16 v[106:109], v[176:179], v[240:243], v[106:109]
	v_mfma_f32_16x16x32_bf16 v[102:105], v[168:171], v[248:251], v[102:105]
	v_mfma_f32_16x16x32_bf16 v[98:101], v[176:179], v[248:251], v[98:101]
	v_mfma_f32_16x16x32_bf16 v[94:97], v[180:183], v[196:199], v[94:97]
	v_mfma_f32_16x16x32_bf16 v[90:93], v[188:191], v[196:199], v[90:93]
	v_mfma_f32_16x16x32_bf16 v[86:89], v[180:183], v[204:207], v[86:89]
	v_mfma_f32_16x16x32_bf16 v[82:85], v[188:191], v[204:207], v[82:85]
	v_mfma_f32_16x16x32_bf16 v[78:81], v[180:183], v[236:239], v[78:81]
	v_mfma_f32_16x16x32_bf16 v[74:77], v[188:191], v[236:239], v[74:77]
	v_mfma_f32_16x16x32_bf16 v[70:73], v[180:183], v[244:247], v[70:73]
	v_mfma_f32_16x16x32_bf16 v[66:69], v[188:191], v[244:247], v[66:69]
	v_mfma_f32_16x16x32_bf16 v[94:97], v[184:187], v[200:203], v[94:97]
	v_mfma_f32_16x16x32_bf16 v[90:93], v[192:195], v[200:203], v[90:93]
	v_mfma_f32_16x16x32_bf16 v[86:89], v[184:187], v[220:223], v[86:89]
	v_mfma_f32_16x16x32_bf16 v[82:85], v[192:195], v[220:223], v[82:85]
	v_mfma_f32_16x16x32_bf16 v[78:81], v[184:187], v[240:243], v[78:81]
	v_mfma_f32_16x16x32_bf16 v[74:77], v[192:195], v[240:243], v[74:77]
	v_mfma_f32_16x16x32_bf16 v[70:73], v[184:187], v[248:251], v[70:73]
	v_mfma_f32_16x16x32_bf16 v[66:69], v[192:195], v[248:251], v[66:69]
	s_barrier
	s_add_i32 s24, s46, s28
	v_lshl_add_u64 v[150:151], v[150:151], 0, s[96:97]
	s_mov_b32 m0, s24
	ds_read_b128 v[196:199], v162 offset:49152
	ds_read_b128 v[200:203], v162 offset:50176
	ds_read_b128 v[204:207], v162 offset:51200
	ds_read_b128 v[220:223], v162 offset:52224
	ds_read_b128 v[236:239], v162 offset:53248
	ds_read_b128 v[240:243], v162 offset:54272
	ds_read_b128 v[244:247], v162 offset:55296
	ds_read_b128 v[248:251], v162 offset:56320
	global_load_lds_dwordx4 v[150:151], off
	s_add_i32 m0, s24, 0x2000
	s_add_u32 s22, s22, 0x40080
	v_lshl_add_u64 v[150:151], v[208:209], 0, s[96:97]
	s_addc_u32 s23, s23, 0
	s_add_i32 s24, s47, s28
	global_load_lds_dwordx4 v[150:151], off
	v_lshl_add_u64 v[150:151], s[22:23], 0, v[134:135]
	s_mov_b32 m0, s24
	s_nop 0
	global_load_lds_dwordx4 v[150:151], off
	v_lshl_add_u64 v[150:151], s[22:23], 0, v[130:131]
	s_add_i32 m0, s24, 0x2000
	s_nop 0
	global_load_lds_dwordx4 v[150:151], off
	v_lshl_add_u64 v[150:151], v[224:225], 0, s[96:97]
	s_mov_b32 m0, s36
	s_nop 0
	global_load_lds_dwordx4 v[150:151], off
	v_lshl_add_u64 v[150:151], v[252:253], 0, s[96:97]
	s_mov_b32 m0, s37
	s_nop 0
	global_load_lds_dwordx4 v[150:151], off
	s_nop 0
	s_nop 0
	s_waitcnt vmcnt(8)
	s_waitcnt lgkmcnt(0)
	s_barrier
	s_waitcnt lgkmcnt(0)
	v_mfma_f32_16x16x32_bf16 v[62:65], v[164:167], v[196:199], v[62:65]
	v_mfma_f32_16x16x32_bf16 v[58:61], v[172:175], v[196:199], v[58:61]
	v_mfma_f32_16x16x32_bf16 v[54:57], v[164:167], v[204:207], v[54:57]
	v_mfma_f32_16x16x32_bf16 v[50:53], v[172:175], v[204:207], v[50:53]
	v_mfma_f32_16x16x32_bf16 v[46:49], v[164:167], v[236:239], v[46:49]
	v_mfma_f32_16x16x32_bf16 v[42:45], v[172:175], v[236:239], v[42:45]
	v_mfma_f32_16x16x32_bf16 v[38:41], v[164:167], v[244:247], v[38:41]
	v_mfma_f32_16x16x32_bf16 v[34:37], v[172:175], v[244:247], v[34:37]
	v_mfma_f32_16x16x32_bf16 v[62:65], v[168:171], v[200:203], v[62:65]
	v_mfma_f32_16x16x32_bf16 v[58:61], v[176:179], v[200:203], v[58:61]
	v_mfma_f32_16x16x32_bf16 v[54:57], v[168:171], v[220:223], v[54:57]
	v_mfma_f32_16x16x32_bf16 v[50:53], v[176:179], v[220:223], v[50:53]
	v_mfma_f32_16x16x32_bf16 v[46:49], v[168:171], v[240:243], v[46:49]
	v_mfma_f32_16x16x32_bf16 v[42:45], v[176:179], v[240:243], v[42:45]
	v_mfma_f32_16x16x32_bf16 v[38:41], v[168:171], v[248:251], v[38:41]
	v_mfma_f32_16x16x32_bf16 v[34:37], v[176:179], v[248:251], v[34:37]
	v_mfma_f32_16x16x32_bf16 v[30:33], v[180:183], v[196:199], v[30:33]
	v_mfma_f32_16x16x32_bf16 v[26:29], v[188:191], v[196:199], v[26:29]
	v_mfma_f32_16x16x32_bf16 v[22:25], v[180:183], v[204:207], v[22:25]
	v_mfma_f32_16x16x32_bf16 v[18:21], v[188:191], v[204:207], v[18:21]
	v_mfma_f32_16x16x32_bf16 v[14:17], v[180:183], v[236:239], v[14:17]
	v_mfma_f32_16x16x32_bf16 v[10:13], v[188:191], v[236:239], v[10:13]
	v_mfma_f32_16x16x32_bf16 v[6:9], v[180:183], v[244:247], v[6:9]
	v_mfma_f32_16x16x32_bf16 v[2:5], v[188:191], v[244:247], v[2:5]
	v_mfma_f32_16x16x32_bf16 v[30:33], v[184:187], v[200:203], v[30:33]
	v_mfma_f32_16x16x32_bf16 v[26:29], v[192:195], v[200:203], v[26:29]
	v_mfma_f32_16x16x32_bf16 v[22:25], v[184:187], v[220:223], v[22:25]
	v_mfma_f32_16x16x32_bf16 v[18:21], v[192:195], v[220:223], v[18:21]
	v_mfma_f32_16x16x32_bf16 v[14:17], v[184:187], v[240:243], v[14:17]
	v_mfma_f32_16x16x32_bf16 v[10:13], v[192:195], v[240:243], v[10:13]
	v_mfma_f32_16x16x32_bf16 v[6:9], v[184:187], v[248:251], v[6:9]
	v_mfma_f32_16x16x32_bf16 v[2:5], v[192:195], v[248:251], v[2:5]
	s_barrier
	s_add_i32 s45, s45, 2
	s_add_u32 s43, s43, 0x100
	s_addc_u32 s44, s44, 0
	s_add_u32 s20, s20, 0x100
	s_addc_u32 s21, s21, 0
	s_cmp_gt_u32 s45, 13
